# v30 + attention fast-path softmax software-pipelined: next pair's subtract issued between exp and sum, two independent row-sum accumulators (f32, same op count +1)
# speedup vs baseline: 1.0053x; 1.0006x over previous
.LBB0_515:
	v_sub_f32_e32 v0, v251, v0
	v_sub_f32_e32 v158, v158, v0
	v_sub_f32_e32 v159, v159, v0
	v_exp_f32_e32 v158, v158
	v_exp_f32_e32 v159, v159
	v_sub_f32_e32 v160, v160, v0
	v_sub_f32_e32 v161, v161, v0
	v_add_f32_e32 v14, 0, v158
	v_add_f32_e32 v15, 0, v159
	v_cvt_pk_bf16_f32 v158, v158, v159
	v_exp_f32_e32 v160, v160
	v_exp_f32_e32 v161, v161
	v_sub_f32_e32 v162, v162, v0
	v_sub_f32_e32 v163, v163, v0
	v_add_f32_e32 v14, v160, v14
	v_add_f32_e32 v15, v161, v15
	v_cvt_pk_bf16_f32 v159, v160, v161
	v_exp_f32_e32 v162, v162
	v_exp_f32_e32 v163, v163
	v_sub_f32_e32 v164, v164, v0
	v_sub_f32_e32 v165, v165, v0
	v_add_f32_e32 v14, v162, v14
	v_add_f32_e32 v15, v163, v15
	v_cvt_pk_bf16_f32 v160, v162, v163
	v_exp_f32_e32 v164, v164
	v_exp_f32_e32 v165, v165
	v_sub_f32_e32 v166, v166, v0
	v_sub_f32_e32 v167, v167, v0
	v_add_f32_e32 v14, v164, v14
	v_add_f32_e32 v15, v165, v15
	v_cvt_pk_bf16_f32 v161, v164, v165
	ds_read_b64_tr_b16 v[162:163], v240 offset:22592
	ds_read_b64_tr_b16 v[164:165], v240 offset:25152
	s_waitcnt lgkmcnt(10)
	v_mfma_f32_32x32x16_bf16 v[64:79], v[2:5], v[158:161], v[64:79]
	ds_read_b64_tr_b16 v[2:3], v240 offset:22656
	ds_read_b64_tr_b16 v[4:5], v240 offset:25216
	v_exp_f32_e32 v166, v166
	v_exp_f32_e32 v167, v167
	v_sub_f32_e32 v168, v168, v0
	v_sub_f32_e32 v169, v169, v0
	v_add_f32_e32 v14, v166, v14
	v_add_f32_e32 v15, v167, v15
	v_cvt_pk_bf16_f32 v166, v166, v167
	s_waitcnt lgkmcnt(10)
	v_mfma_f32_32x32x16_bf16 v[48:63], v[6:9], v[158:161], v[48:63]
	ds_read_b64_tr_b16 v[6:7], v240 offset:22720
	ds_read_b64_tr_b16 v[8:9], v240 offset:25280
	v_exp_f32_e32 v168, v168
	v_exp_f32_e32 v169, v169
	v_sub_f32_e32 v170, v170, v0
	v_sub_f32_e32 v171, v171, v0
	v_add_f32_e32 v14, v168, v14
	v_add_f32_e32 v15, v169, v15
	v_cvt_pk_bf16_f32 v167, v168, v169
	s_waitcnt lgkmcnt(10)
	v_mfma_f32_32x32x16_bf16 v[32:47], v[10:13], v[158:161], v[32:47]
	ds_read_b64_tr_b16 v[10:11], v240 offset:27648
	ds_read_b64_tr_b16 v[12:13], v240 offset:30208
	v_exp_f32_e32 v170, v170
	v_exp_f32_e32 v171, v171
	v_sub_f32_e32 v172, v172, v0
	v_sub_f32_e32 v173, v173, v0
	v_add_f32_e32 v14, v170, v14
	v_add_f32_e32 v15, v171, v15
	v_cvt_pk_bf16_f32 v168, v170, v171
	s_waitcnt lgkmcnt(10)
	v_mfma_f32_32x32x16_bf16 v[16:31], v[208:211], v[158:161], v[16:31]
	ds_read_b64_tr_b16 v[208:209], v240 offset:27712
	ds_read_b64_tr_b16 v[210:211], v240 offset:30272
	v_exp_f32_e32 v172, v172
	v_exp_f32_e32 v173, v173
	v_sub_f32_e32 v142, v142, v0
	v_sub_f32_e32 v143, v143, v0
	v_add_f32_e32 v14, v172, v14
	v_add_f32_e32 v15, v173, v15
	v_cvt_pk_bf16_f32 v169, v172, v173
	ds_read_b64_tr_b16 v[170:171], v240 offset:27776
	ds_read_b64_tr_b16 v[172:173], v240 offset:30336
	s_waitcnt lgkmcnt(12)
	v_mfma_f32_32x32x16_bf16 v[64:79], v[212:215], v[166:169], v[64:79]
	ds_read_b64_tr_b16 v[212:213], v240 offset:27840
	ds_read_b64_tr_b16 v[214:215], v240 offset:30400
	v_exp_f32_e32 v142, v142
	v_exp_f32_e32 v143, v143
	v_sub_f32_e32 v144, v144, v0
	v_sub_f32_e32 v145, v145, v0
	v_add_f32_e32 v14, v142, v14
	v_add_f32_e32 v15, v143, v15
	v_cvt_pk_bf16_f32 v142, v142, v143
	s_waitcnt lgkmcnt(12)
	v_mfma_f32_32x32x16_bf16 v[48:63], v[162:165], v[166:169], v[48:63]
	ds_read_b64_tr_b16 v[162:163], v240 offset:32768
	ds_read_b64_tr_b16 v[164:165], v240 offset:35328
	v_exp_f32_e32 v144, v144
	v_exp_f32_e32 v145, v145
	v_sub_f32_e32 v146, v146, v0
	v_sub_f32_e32 v147, v147, v0
	v_add_f32_e32 v14, v144, v14
	v_add_f32_e32 v15, v145, v15
	v_cvt_pk_bf16_f32 v143, v144, v145
	s_waitcnt lgkmcnt(12)
	v_mfma_f32_32x32x16_bf16 v[32:47], v[2:5], v[166:169], v[32:47]
	ds_read_b64_tr_b16 v[2:3], v240 offset:32832
	ds_read_b64_tr_b16 v[4:5], v240 offset:35392
	v_exp_f32_e32 v146, v146
	v_exp_f32_e32 v147, v147
	v_sub_f32_e32 v148, v148, v0
	v_sub_f32_e32 v149, v149, v0
	v_add_f32_e32 v14, v146, v14
	v_add_f32_e32 v15, v147, v15
	v_cvt_pk_bf16_f32 v144, v146, v147
	s_waitcnt lgkmcnt(12)
	v_mfma_f32_32x32x16_bf16 v[16:31], v[6:9], v[166:169], v[16:31]
	ds_read_b64_tr_b16 v[6:7], v240 offset:32896
	ds_read_b64_tr_b16 v[8:9], v240 offset:35456
	v_exp_f32_e32 v148, v148
	v_exp_f32_e32 v149, v149
	v_sub_f32_e32 v150, v150, v0
	v_sub_f32_e32 v151, v151, v0
	v_add_f32_e32 v14, v148, v14
	v_add_f32_e32 v15, v149, v15
	v_cvt_pk_bf16_f32 v145, v148, v149
	ds_read_b64_tr_b16 v[146:147], v240 offset:32960
	ds_read_b64_tr_b16 v[148:149], v240 offset:35520
	s_waitcnt lgkmcnt(14)
	v_mfma_f32_32x32x16_bf16 v[64:79], v[10:13], v[142:145], v[64:79]
	v_exp_f32_e32 v150, v150
	v_exp_f32_e32 v151, v151
	v_sub_f32_e32 v152, v152, v0
	v_sub_f32_e32 v153, v153, v0
	v_add_f32_e32 v14, v150, v14
	v_add_f32_e32 v15, v151, v15
	v_cvt_pk_bf16_f32 v150, v150, v151
	s_waitcnt lgkmcnt(12)
	v_mfma_f32_32x32x16_bf16 v[48:63], v[208:211], v[142:145], v[48:63]
	v_exp_f32_e32 v152, v152
	v_exp_f32_e32 v153, v153
	v_sub_f32_e32 v154, v154, v0
	v_sub_f32_e32 v155, v155, v0
	v_add_f32_e32 v14, v152, v14
	v_add_f32_e32 v15, v153, v15
	v_cvt_pk_bf16_f32 v151, v152, v153
	s_waitcnt lgkmcnt(10)
	v_mfma_f32_32x32x16_bf16 v[32:47], v[170:173], v[142:145], v[32:47]
	v_exp_f32_e32 v154, v154
	v_exp_f32_e32 v155, v155
	v_sub_f32_e32 v156, v156, v0
	v_sub_f32_e32 v157, v157, v0
	v_add_f32_e32 v14, v154, v14
	v_add_f32_e32 v15, v155, v15
	v_cvt_pk_bf16_f32 v152, v154, v155
	s_waitcnt lgkmcnt(8)
	v_mfma_f32_32x32x16_bf16 v[16:31], v[212:215], v[142:145], v[16:31]
	v_exp_f32_e32 v156, v156
	v_exp_f32_e32 v157, v157
	s_nop 0
	v_add_f32_e32 v14, v156, v14
	v_add_f32_e32 v15, v157, v15
	v_cvt_pk_bf16_f32 v153, v156, v157
	v_add_f32_e32 v14, v14, v15
	v_add_f32_e32 v250, v250, v14
	s_andn2_b64 vcc, exec, s[20:21]
	s_cbranch_vccnz .Lattn_pv3_nostore
	s_andn2_b32 s101, 1, s25
	s_mul_i32 s101, s101, 0x9400
	v_add_u32_e32 v14, s101, v221
	v_add_u32_e32 v15, v14, v242
	v_add_u32_e32 v239, v14, v241
	v_add_u32_e32 v252, v14, v225
	v_add_u32_e32 v14, v14, v223
	s_waitcnt vmcnt(3)
	ds_write_b128 v14, v[190:193]
	s_waitcnt vmcnt(2)
	ds_write_b128 v239, v[198:201]
	s_waitcnt vmcnt(1)
	ds_write_b128 v252, v[194:197] offset:17408
	s_waitcnt vmcnt(0)
	ds_write_b128 v15, v[202:205] offset:17408
	s_waitcnt lgkmcnt(10)
	v_mfma_f32_32x32x16_bf16 v[64:79], v[162:165], v[150:153], v[64:79]
	s_waitcnt lgkmcnt(8)
	v_mfma_f32_32x32x16_bf16 v[48:63], v[2:5], v[150:153], v[48:63]
	s_waitcnt lgkmcnt(6)
	v_mfma_f32_32x32x16_bf16 v[32:47], v[6:9], v[150:153], v[32:47]
	s_waitcnt lgkmcnt(4)
	v_mfma_f32_32x32x16_bf16 v[16:31], v[146:149], v[150:153], v[16:31]
	s_branch .LBB0_505
